# proj epilogue 1: all 16 gate loads issued up front into dead fragment registers, counted vmcnt(15) per step (was a 16-round-trip ladder)
# speedup vs baseline: 1.0188x; 1.0036x over previous
.LBB0_541:
	s_or_b64 exec, exec, s[4:5]
	v_mov_b32_e32 v132, v154
	s_mov_b64 s[12:13], 0x8d00800
	v_ashrrev_i32_e32 v128, 2, v132
	v_and_b32_e32 v130, 15, v132
	v_and_b32_e32 v128, 0xffffffc0, v128
	v_ashrrev_i32_e32 v129, 31, v128
	v_lshl_or_b32 v136, s10, 8, v130
	v_lshl_add_u64 v[130:131], v[136:137], 0, v[128:129]
	v_lshrrev_b32_e32 v128, 1, v132
	v_and_b32_e32 v128, 0x78, v128
	v_lshl_or_b32 v146, s0, 8, v128
	v_mov_b64_e32 v[132:133], s[72:73]
	s_movk_i32 s10, 0x1800
	v_mad_i64_i32 v[134:135], s[0:1], v130, s10, v[132:133]
	v_ashrrev_i32_e32 v147, 31, v146
	v_lshl_add_u64 v[148:149], v[134:135], 0, s[12:13]
	v_lshlrev_b64 v[128:129], 1, v[146:147]
	v_lshl_add_u64 v[140:141], v[148:149], 0, v[128:129]
	v_lshl_add_u64 v[242:243], v[134:135], 0, v[128:129]
	s_mov_b64 s[92:93], 0x8d00800
	v_lshl_add_u64 v[244:245], v[242:243], 0, s[92:93]
	global_load_dwordx4 v[178:181], v[244:245], off
	global_load_dwordx4 v[182:185], v[244:245], off offset:256
	s_mov_b64 s[92:93], 0x8d18800
	v_lshl_add_u64 v[244:245], v[242:243], 0, s[92:93]
	global_load_dwordx4 v[186:189], v[244:245], off
	global_load_dwordx4 v[190:193], v[244:245], off offset:256
	s_mov_b64 s[92:93], 0x8d30800
	v_lshl_add_u64 v[244:245], v[242:243], 0, s[92:93]
	global_load_dwordx4 v[194:197], v[244:245], off
	global_load_dwordx4 v[198:201], v[244:245], off offset:256
	s_mov_b64 s[92:93], 0x8d48800
	v_lshl_add_u64 v[244:245], v[242:243], 0, s[92:93]
	global_load_dwordx4 v[202:205], v[244:245], off
	global_load_dwordx4 v[206:209], v[244:245], off offset:256
	s_mov_b64 s[92:93], 0x8dc0800
	v_lshl_add_u64 v[244:245], v[242:243], 0, s[92:93]
	global_load_dwordx4 v[210:213], v[244:245], off
	global_load_dwordx4 v[214:217], v[244:245], off offset:256
	s_mov_b64 s[92:93], 0x8dd8800
	v_lshl_add_u64 v[244:245], v[242:243], 0, s[92:93]
	global_load_dwordx4 v[218:221], v[244:245], off
	global_load_dwordx4 v[222:225], v[244:245], off offset:256
	s_mov_b64 s[92:93], 0x8df0800
	v_lshl_add_u64 v[244:245], v[242:243], 0, s[92:93]
	global_load_dwordx4 v[226:229], v[244:245], off
	global_load_dwordx4 v[230:233], v[244:245], off offset:256
	s_mov_b64 s[92:93], 0x8e08800
	v_lshl_add_u64 v[244:245], v[242:243], 0, s[92:93]
	global_load_dwordx4 v[234:237], v[244:245], off
	global_load_dwordx4 v[238:241], v[244:245], off offset:256
	v_readlane_b32 s4, v254, 19
	v_lshlrev_b64 v[144:145], 11, v[130:131]
	v_readlane_b32 s5, v254, 20
	s_waitcnt vmcnt(15)
	v_lshlrev_b32_e32 v136, 16, v178
	v_mul_f32_e32 v136, 0xbfb8aa3b, v136
	v_exp_f32_e32 v136, v136
	v_and_b32_e32 v139, 0xffff0000, v178
	v_lshlrev_b32_e32 v147, 16, v179
	v_and_b32_e32 v152, 0xffff0000, v179
	v_add_f32_e32 v136, 1.0, v136
	v_rcp_f32_e32 v140, v136
	v_mul_f32_e32 v136, 0xbfb8aa3b, v139
	v_exp_f32_e32 v136, v136
	v_lshlrev_b32_e32 v153, 16, v180
	v_and_b32_e32 v142, 0xffff0000, v180
	v_lshlrev_b32_e32 v162, 16, v181
	v_add_f32_e32 v136, 1.0, v136
	v_rcp_f32_e32 v141, v136
	v_mul_f32_e32 v136, 0xbfb8aa3b, v147
	v_exp_f32_e32 v136, v136
	v_and_b32_e32 v143, 0xffff0000, v181
	v_pk_mul_f32 v[124:125], v[124:125], v[140:141]
	v_lshl_add_u64 v[150:151], s[4:5], 0, v[144:145]
	v_add_f32_e32 v136, 1.0, v136
	v_rcp_f32_e32 v140, v136
	v_mul_f32_e32 v136, 0xbfb8aa3b, v152
	v_exp_f32_e32 v136, v136
	v_cvt_pk_bf16_f32 v124, v124, v125
	v_add_f32_e32 v136, 1.0, v136
	v_rcp_f32_e32 v141, v136
	v_mul_f32_e32 v136, 0xbfb8aa3b, v153
	v_exp_f32_e32 v136, v136
	v_pk_mul_f32 v[126:127], v[126:127], v[140:141]
	s_nop 0
	v_cvt_pk_bf16_f32 v125, v126, v127
	v_add_f32_e32 v136, 1.0, v136
	v_rcp_f32_e32 v140, v136
	v_mul_f32_e32 v136, 0xbfb8aa3b, v142
	v_exp_f32_e32 v136, v136
	s_nop 0
	v_add_f32_e32 v136, 1.0, v136
	v_rcp_f32_e32 v141, v136
	v_mul_f32_e32 v136, 0xbfb8aa3b, v162
	v_exp_f32_e32 v136, v136
	v_pk_mul_f32 v[120:121], v[120:121], v[140:141]
	s_nop 0
	v_cvt_pk_bf16_f32 v126, v120, v121
	v_add_f32_e32 v136, 1.0, v136
	v_rcp_f32_e32 v140, v136
	v_mul_f32_e32 v136, 0xbfb8aa3b, v143
	v_exp_f32_e32 v136, v136
	v_or_b32_e32 v120, 0x80, v146
	v_ashrrev_i32_e32 v121, 31, v120
	v_lshlrev_b64 v[120:121], 1, v[120:121]
	v_add_f32_e32 v136, 1.0, v136
	v_rcp_f32_e32 v141, v136
	s_nop 0
	v_pk_mul_f32 v[122:123], v[122:123], v[140:141]
	s_nop 0
	v_cvt_pk_bf16_f32 v127, v122, v123
	v_lshl_add_u64 v[122:123], v[150:151], 0, v[128:129]
	global_store_dwordx4 v[122:123], v[124:127], off
	s_nop 1
	v_lshl_add_u64 v[124:125], v[148:149], 0, v[120:121]
	s_waitcnt vmcnt(15)
	v_lshlrev_b32_e32 v136, 16, v182
	v_and_b32_e32 v139, 0xffff0000, v182
	v_lshlrev_b32_e32 v140, 16, v183
	v_and_b32_e32 v141, 0xffff0000, v183
	v_mul_f32_e32 v124, 0xbfb8aa3b, v136
	v_mul_f32_e32 v125, 0xbfb8aa3b, v139
	v_exp_f32_e32 v124, v124
	v_exp_f32_e32 v125, v125
	v_lshlrev_b32_e32 v142, 16, v184
	v_and_b32_e32 v126, 0xffff0000, v184
	v_add_f32_e32 v124, 1.0, v124
	v_add_f32_e32 v125, 1.0, v125
	v_rcp_f32_e32 v124, v124
	v_rcp_f32_e32 v125, v125
	v_lshlrev_b32_e32 v143, 16, v185
	v_and_b32_e32 v127, 0xffff0000, v185
	v_pk_mul_f32 v[116:117], v[116:117], v[124:125]
	v_mul_f32_e32 v124, 0xbfb8aa3b, v140
	v_mul_f32_e32 v125, 0xbfb8aa3b, v141
	v_exp_f32_e32 v124, v124
	v_exp_f32_e32 v125, v125
	v_add_f32_e32 v124, 1.0, v124
	v_add_f32_e32 v125, 1.0, v125
	v_rcp_f32_e32 v124, v124
	v_rcp_f32_e32 v125, v125
	s_nop 0
	v_pk_mul_f32 v[118:119], v[118:119], v[124:125]
	v_mul_f32_e32 v124, 0xbfb8aa3b, v142
	v_mul_f32_e32 v125, 0xbfb8aa3b, v126
	v_exp_f32_e32 v124, v124
	v_exp_f32_e32 v125, v125
	v_add_f32_e32 v124, 1.0, v124
	v_add_f32_e32 v125, 1.0, v125
	v_rcp_f32_e32 v124, v124
	v_rcp_f32_e32 v125, v125
	s_nop 0
	v_pk_mul_f32 v[124:125], v[112:113], v[124:125]
	v_mul_f32_e32 v112, 0xbfb8aa3b, v143
	v_mul_f32_e32 v113, 0xbfb8aa3b, v127
	v_exp_f32_e32 v112, v112
	v_exp_f32_e32 v113, v113
	v_add_f32_e32 v112, 1.0, v112
	v_add_f32_e32 v113, 1.0, v113
	v_rcp_f32_e32 v112, v112
	v_rcp_f32_e32 v113, v113
	s_nop 0
	v_pk_mul_f32 v[126:127], v[114:115], v[112:113]
	v_cvt_pk_bf16_f32 v112, v116, v117
	v_cvt_pk_bf16_f32 v113, v118, v119
	v_cvt_pk_bf16_f32 v114, v124, v125
	v_cvt_pk_bf16_f32 v115, v126, v127
	global_store_dwordx4 v[122:123], v[112:115], off offset:256
	s_mov_b64 s[14:15], 0x8d18800
	v_lshl_add_u64 v[116:117], v[134:135], 0, s[14:15]
	v_or_b32_e32 v112, 0x8000, v144
	v_mov_b32_e32 v113, v145
	v_lshl_add_u64 v[118:119], s[4:5], 0, v[112:113]
	v_lshl_add_u64 v[112:113], v[116:117], 0, v[128:129]
	s_waitcnt vmcnt(15)
	v_lshlrev_b32_e32 v124, 16, v186
	v_and_b32_e32 v125, 0xffff0000, v186
	v_lshlrev_b32_e32 v126, 16, v187
	v_and_b32_e32 v127, 0xffff0000, v187
	v_mul_f32_e32 v112, 0xbfb8aa3b, v124
	v_mul_f32_e32 v113, 0xbfb8aa3b, v125
	v_exp_f32_e32 v112, v112
	v_exp_f32_e32 v113, v113
	v_lshlrev_b32_e32 v136, 16, v188
	v_and_b32_e32 v114, 0xffff0000, v188
	v_add_f32_e32 v112, 1.0, v112
	v_add_f32_e32 v113, 1.0, v113
	v_rcp_f32_e32 v112, v112
	v_rcp_f32_e32 v113, v113
	v_lshlrev_b32_e32 v139, 16, v189
	v_and_b32_e32 v115, 0xffff0000, v189
	v_pk_mul_f32 v[108:109], v[108:109], v[112:113]
	v_mul_f32_e32 v112, 0xbfb8aa3b, v126
	v_mul_f32_e32 v113, 0xbfb8aa3b, v127
	v_exp_f32_e32 v112, v112
	v_exp_f32_e32 v113, v113
	v_add_f32_e32 v112, 1.0, v112
	v_add_f32_e32 v113, 1.0, v113
	v_rcp_f32_e32 v112, v112
	v_rcp_f32_e32 v113, v113
	s_nop 0
	v_pk_mul_f32 v[110:111], v[110:111], v[112:113]
	v_mul_f32_e32 v112, 0xbfb8aa3b, v136
	v_mul_f32_e32 v113, 0xbfb8aa3b, v114
	v_exp_f32_e32 v112, v112
	v_exp_f32_e32 v113, v113
	v_add_f32_e32 v112, 1.0, v112
	v_add_f32_e32 v113, 1.0, v113
	v_rcp_f32_e32 v112, v112
	v_rcp_f32_e32 v113, v113
	s_nop 0
	v_pk_mul_f32 v[104:105], v[104:105], v[112:113]
	v_mul_f32_e32 v112, 0xbfb8aa3b, v139
	v_mul_f32_e32 v113, 0xbfb8aa3b, v115
	v_exp_f32_e32 v112, v112
	v_exp_f32_e32 v113, v113
	v_add_f32_e32 v112, 1.0, v112
	v_add_f32_e32 v113, 1.0, v113
	v_rcp_f32_e32 v112, v112
	v_rcp_f32_e32 v113, v113
	s_nop 0
	v_pk_mul_f32 v[112:113], v[106:107], v[112:113]
	v_cvt_pk_bf16_f32 v106, v108, v109
	v_cvt_pk_bf16_f32 v107, v110, v111
	v_cvt_pk_bf16_f32 v108, v104, v105
	v_cvt_pk_bf16_f32 v109, v112, v113
	v_lshl_add_u64 v[104:105], v[118:119], 0, v[128:129]
	global_store_dwordx4 v[104:105], v[106:109], off
	s_nop 1
	v_lshl_add_u64 v[106:107], v[116:117], 0, v[120:121]
	s_waitcnt vmcnt(15)
	v_lshlrev_b32_e32 v110, 16, v190
	v_and_b32_e32 v111, 0xffff0000, v190
	v_lshlrev_b32_e32 v112, 16, v191
	v_and_b32_e32 v113, 0xffff0000, v191
	v_mul_f32_e32 v106, 0xbfb8aa3b, v110
	v_mul_f32_e32 v107, 0xbfb8aa3b, v111
	v_exp_f32_e32 v106, v106
	v_exp_f32_e32 v107, v107
	v_lshlrev_b32_e32 v114, 16, v192
	v_and_b32_e32 v108, 0xffff0000, v192
	v_add_f32_e32 v106, 1.0, v106
	v_add_f32_e32 v107, 1.0, v107
	v_rcp_f32_e32 v106, v106
	v_rcp_f32_e32 v107, v107
	v_lshlrev_b32_e32 v115, 16, v193
	v_and_b32_e32 v109, 0xffff0000, v193
	v_pk_mul_f32 v[100:101], v[100:101], v[106:107]
	v_mul_f32_e32 v106, 0xbfb8aa3b, v112
	v_mul_f32_e32 v107, 0xbfb8aa3b, v113
	v_exp_f32_e32 v106, v106
	v_exp_f32_e32 v107, v107
	v_add_f32_e32 v106, 1.0, v106
	v_add_f32_e32 v107, 1.0, v107
	v_rcp_f32_e32 v106, v106
	v_rcp_f32_e32 v107, v107
	s_nop 0
	v_pk_mul_f32 v[102:103], v[102:103], v[106:107]
	v_mul_f32_e32 v106, 0xbfb8aa3b, v114
	v_mul_f32_e32 v107, 0xbfb8aa3b, v108
	v_exp_f32_e32 v106, v106
	v_exp_f32_e32 v107, v107
	v_add_f32_e32 v106, 1.0, v106
	v_add_f32_e32 v107, 1.0, v107
	v_rcp_f32_e32 v106, v106
	v_rcp_f32_e32 v107, v107
	s_nop 0
	v_pk_mul_f32 v[106:107], v[96:97], v[106:107]
	v_mul_f32_e32 v96, 0xbfb8aa3b, v115
	v_mul_f32_e32 v97, 0xbfb8aa3b, v109
	v_exp_f32_e32 v96, v96
	v_exp_f32_e32 v97, v97
	v_add_f32_e32 v96, 1.0, v96
	v_add_f32_e32 v97, 1.0, v97
	v_rcp_f32_e32 v96, v96
	v_rcp_f32_e32 v97, v97
	s_nop 0
	v_pk_mul_f32 v[108:109], v[98:99], v[96:97]
	v_cvt_pk_bf16_f32 v96, v100, v101
	v_cvt_pk_bf16_f32 v97, v102, v103
	v_cvt_pk_bf16_f32 v98, v106, v107
	v_cvt_pk_bf16_f32 v99, v108, v109
	global_store_dwordx4 v[104:105], v[96:99], off offset:256
	s_mov_b64 s[26:27], 0x8d30800
	v_lshl_add_u64 v[100:101], v[134:135], 0, s[26:27]
	v_or_b32_e32 v96, 0x10000, v144
	v_mov_b32_e32 v97, v145
	v_lshl_add_u64 v[102:103], s[4:5], 0, v[96:97]
	v_lshl_add_u64 v[96:97], v[100:101], 0, v[128:129]
	s_waitcnt vmcnt(15)
	v_lshlrev_b32_e32 v104, 16, v194
	v_and_b32_e32 v105, 0xffff0000, v194
	v_lshlrev_b32_e32 v106, 16, v195
	v_and_b32_e32 v107, 0xffff0000, v195
	v_mul_f32_e32 v96, 0xbfb8aa3b, v104
	v_mul_f32_e32 v97, 0xbfb8aa3b, v105
	v_exp_f32_e32 v96, v96
	v_exp_f32_e32 v97, v97
	v_lshlrev_b32_e32 v108, 16, v196
	v_and_b32_e32 v98, 0xffff0000, v196
	v_add_f32_e32 v96, 1.0, v96
	v_add_f32_e32 v97, 1.0, v97
	v_rcp_f32_e32 v96, v96
	v_rcp_f32_e32 v97, v97
	v_lshlrev_b32_e32 v109, 16, v197
	v_and_b32_e32 v99, 0xffff0000, v197
	v_pk_mul_f32 v[92:93], v[92:93], v[96:97]
	v_mul_f32_e32 v96, 0xbfb8aa3b, v106
	v_mul_f32_e32 v97, 0xbfb8aa3b, v107
	v_exp_f32_e32 v96, v96
	v_exp_f32_e32 v97, v97
	v_add_f32_e32 v96, 1.0, v96
	v_add_f32_e32 v97, 1.0, v97
	v_rcp_f32_e32 v96, v96
	v_rcp_f32_e32 v97, v97
	s_nop 0
	v_pk_mul_f32 v[94:95], v[94:95], v[96:97]
	v_mul_f32_e32 v96, 0xbfb8aa3b, v108
	v_mul_f32_e32 v97, 0xbfb8aa3b, v98
	v_exp_f32_e32 v96, v96
	v_exp_f32_e32 v97, v97
	v_add_f32_e32 v96, 1.0, v96
	v_add_f32_e32 v97, 1.0, v97
	v_rcp_f32_e32 v96, v96
	v_rcp_f32_e32 v97, v97
	s_nop 0
	v_pk_mul_f32 v[88:89], v[88:89], v[96:97]
	v_mul_f32_e32 v96, 0xbfb8aa3b, v109
	v_mul_f32_e32 v97, 0xbfb8aa3b, v99
	v_exp_f32_e32 v96, v96
	v_exp_f32_e32 v97, v97
	v_add_f32_e32 v96, 1.0, v96
	v_add_f32_e32 v97, 1.0, v97
	v_rcp_f32_e32 v96, v96
	v_rcp_f32_e32 v97, v97
	s_nop 0
	v_pk_mul_f32 v[96:97], v[90:91], v[96:97]
	v_cvt_pk_bf16_f32 v90, v92, v93
	v_cvt_pk_bf16_f32 v91, v94, v95
	v_cvt_pk_bf16_f32 v92, v88, v89
	v_cvt_pk_bf16_f32 v93, v96, v97
	v_lshl_add_u64 v[88:89], v[102:103], 0, v[128:129]
	global_store_dwordx4 v[88:89], v[90:93], off
	s_nop 1
	v_lshl_add_u64 v[90:91], v[100:101], 0, v[120:121]
	s_waitcnt vmcnt(15)
	v_lshlrev_b32_e32 v94, 16, v198
	v_and_b32_e32 v95, 0xffff0000, v198
	v_lshlrev_b32_e32 v96, 16, v199
	v_and_b32_e32 v97, 0xffff0000, v199
	v_mul_f32_e32 v90, 0xbfb8aa3b, v94
	v_mul_f32_e32 v91, 0xbfb8aa3b, v95
	v_exp_f32_e32 v90, v90
	v_exp_f32_e32 v91, v91
	v_lshlrev_b32_e32 v98, 16, v200
	v_and_b32_e32 v92, 0xffff0000, v200
	v_add_f32_e32 v90, 1.0, v90
	v_add_f32_e32 v91, 1.0, v91
	v_rcp_f32_e32 v90, v90
	v_rcp_f32_e32 v91, v91
	v_lshlrev_b32_e32 v99, 16, v201
	v_and_b32_e32 v93, 0xffff0000, v201
	v_pk_mul_f32 v[84:85], v[84:85], v[90:91]
	v_mul_f32_e32 v90, 0xbfb8aa3b, v96
	v_mul_f32_e32 v91, 0xbfb8aa3b, v97
	v_exp_f32_e32 v90, v90
	v_exp_f32_e32 v91, v91
	v_add_f32_e32 v90, 1.0, v90
	v_add_f32_e32 v91, 1.0, v91
	v_rcp_f32_e32 v90, v90
	v_rcp_f32_e32 v91, v91
	s_nop 0
	v_pk_mul_f32 v[86:87], v[86:87], v[90:91]
	v_mul_f32_e32 v90, 0xbfb8aa3b, v98
	v_mul_f32_e32 v91, 0xbfb8aa3b, v92
	v_exp_f32_e32 v90, v90
	v_exp_f32_e32 v91, v91
	v_add_f32_e32 v90, 1.0, v90
	v_add_f32_e32 v91, 1.0, v91
	v_rcp_f32_e32 v90, v90
	v_rcp_f32_e32 v91, v91
	s_nop 0
	v_pk_mul_f32 v[90:91], v[80:81], v[90:91]
	v_mul_f32_e32 v80, 0xbfb8aa3b, v99
	v_mul_f32_e32 v81, 0xbfb8aa3b, v93
	v_exp_f32_e32 v80, v80
	v_exp_f32_e32 v81, v81
	v_add_f32_e32 v80, 1.0, v80
	v_add_f32_e32 v81, 1.0, v81
	v_rcp_f32_e32 v80, v80
	v_rcp_f32_e32 v81, v81
	s_nop 0
	v_pk_mul_f32 v[92:93], v[82:83], v[80:81]
	v_cvt_pk_bf16_f32 v80, v84, v85
	v_cvt_pk_bf16_f32 v81, v86, v87
	v_cvt_pk_bf16_f32 v82, v90, v91
	v_cvt_pk_bf16_f32 v83, v92, v93
	global_store_dwordx4 v[88:89], v[80:83], off offset:256
	s_mov_b64 s[0:1], 0x8d48800
	v_lshl_add_u64 v[84:85], v[134:135], 0, s[0:1]
	v_lshl_add_u64 v[80:81], v[84:85], 0, v[128:129]
	v_or_b32_e32 v144, 0x18000, v144
	v_lshl_add_u64 v[86:87], s[4:5], 0, v[144:145]
	s_waitcnt vmcnt(15)
	v_lshlrev_b32_e32 v88, 16, v202
	v_and_b32_e32 v89, 0xffff0000, v202
	v_lshlrev_b32_e32 v90, 16, v203
	v_and_b32_e32 v91, 0xffff0000, v203
	v_mul_f32_e32 v80, 0xbfb8aa3b, v88
	v_mul_f32_e32 v81, 0xbfb8aa3b, v89
	v_exp_f32_e32 v80, v80
	v_exp_f32_e32 v81, v81
	v_lshlrev_b32_e32 v92, 16, v204
	v_and_b32_e32 v82, 0xffff0000, v204
	v_add_f32_e32 v80, 1.0, v80
	v_add_f32_e32 v81, 1.0, v81
	v_rcp_f32_e32 v80, v80
	v_rcp_f32_e32 v81, v81
	v_lshlrev_b32_e32 v93, 16, v205
	v_and_b32_e32 v83, 0xffff0000, v205
	v_pk_mul_f32 v[76:77], v[76:77], v[80:81]
	v_mul_f32_e32 v80, 0xbfb8aa3b, v90
	v_mul_f32_e32 v81, 0xbfb8aa3b, v91
	v_exp_f32_e32 v80, v80
	v_exp_f32_e32 v81, v81
	v_add_f32_e32 v80, 1.0, v80
	v_add_f32_e32 v81, 1.0, v81
	v_rcp_f32_e32 v80, v80
	v_rcp_f32_e32 v81, v81
	s_nop 0
	v_pk_mul_f32 v[78:79], v[78:79], v[80:81]
	v_mul_f32_e32 v80, 0xbfb8aa3b, v92
	v_mul_f32_e32 v81, 0xbfb8aa3b, v82
	v_exp_f32_e32 v80, v80
	v_exp_f32_e32 v81, v81
	v_add_f32_e32 v80, 1.0, v80
	v_add_f32_e32 v81, 1.0, v81
	v_rcp_f32_e32 v80, v80
	v_rcp_f32_e32 v81, v81
	s_nop 0
	v_pk_mul_f32 v[72:73], v[72:73], v[80:81]
	v_mul_f32_e32 v80, 0xbfb8aa3b, v93
	v_mul_f32_e32 v81, 0xbfb8aa3b, v83
	v_exp_f32_e32 v80, v80
	v_exp_f32_e32 v81, v81
	v_add_f32_e32 v80, 1.0, v80
	v_add_f32_e32 v81, 1.0, v81
	v_rcp_f32_e32 v80, v80
	v_rcp_f32_e32 v81, v81
	s_nop 0
	v_pk_mul_f32 v[80:81], v[74:75], v[80:81]
	v_cvt_pk_bf16_f32 v74, v76, v77
	v_cvt_pk_bf16_f32 v75, v78, v79
	v_cvt_pk_bf16_f32 v76, v72, v73
	v_cvt_pk_bf16_f32 v77, v80, v81
	v_lshl_add_u64 v[72:73], v[86:87], 0, v[128:129]
	global_store_dwordx4 v[72:73], v[74:77], off
	s_nop 1
	v_lshl_add_u64 v[74:75], v[84:85], 0, v[120:121]
	s_waitcnt vmcnt(15)
	v_lshlrev_b32_e32 v78, 16, v206
	v_and_b32_e32 v79, 0xffff0000, v206
	v_lshlrev_b32_e32 v80, 16, v207
	v_and_b32_e32 v81, 0xffff0000, v207
	v_mul_f32_e32 v74, 0xbfb8aa3b, v78
	v_mul_f32_e32 v75, 0xbfb8aa3b, v79
	v_exp_f32_e32 v74, v74
	v_exp_f32_e32 v75, v75
	v_lshlrev_b32_e32 v82, 16, v208
	v_and_b32_e32 v76, 0xffff0000, v208
	v_add_f32_e32 v74, 1.0, v74
	v_add_f32_e32 v75, 1.0, v75
	v_rcp_f32_e32 v74, v74
	v_rcp_f32_e32 v75, v75
	v_lshlrev_b32_e32 v83, 16, v209
	v_and_b32_e32 v77, 0xffff0000, v209
	v_pk_mul_f32 v[68:69], v[68:69], v[74:75]
	v_mul_f32_e32 v74, 0xbfb8aa3b, v80
	v_mul_f32_e32 v75, 0xbfb8aa3b, v81
	v_exp_f32_e32 v74, v74
	v_exp_f32_e32 v75, v75
	v_add_f32_e32 v74, 1.0, v74
	v_add_f32_e32 v75, 1.0, v75
	v_rcp_f32_e32 v74, v74
	v_rcp_f32_e32 v75, v75
	s_nop 0
	v_pk_mul_f32 v[70:71], v[70:71], v[74:75]
	v_mul_f32_e32 v74, 0xbfb8aa3b, v82
	v_mul_f32_e32 v75, 0xbfb8aa3b, v76
	v_exp_f32_e32 v74, v74
	v_exp_f32_e32 v75, v75
	v_add_f32_e32 v74, 1.0, v74
	v_add_f32_e32 v75, 1.0, v75
	v_rcp_f32_e32 v74, v74
	v_rcp_f32_e32 v75, v75
	s_nop 0
	v_pk_mul_f32 v[74:75], v[64:65], v[74:75]
	v_mul_f32_e32 v64, 0xbfb8aa3b, v83
	v_mul_f32_e32 v65, 0xbfb8aa3b, v77
	v_exp_f32_e32 v64, v64
	v_exp_f32_e32 v65, v65
	v_add_f32_e32 v64, 1.0, v64
	v_add_f32_e32 v65, 1.0, v65
	v_rcp_f32_e32 v64, v64
	v_rcp_f32_e32 v65, v65
	s_nop 0
	v_pk_mul_f32 v[76:77], v[66:67], v[64:65]
	v_cvt_pk_bf16_f32 v64, v68, v69
	v_cvt_pk_bf16_f32 v65, v70, v71
	v_cvt_pk_bf16_f32 v66, v74, v75
	v_cvt_pk_bf16_f32 v67, v76, v77
	global_store_dwordx4 v[72:73], v[64:67], off offset:256
	s_mov_b64 s[0:1], 0x8dc0800
	v_lshl_add_u64 v[68:69], v[134:135], 0, s[0:1]
	v_lshl_add_u64 v[64:65], v[68:69], 0, v[128:129]
	s_mov_b64 s[0:1], 0x40000
	s_waitcnt vmcnt(15)
	v_lshlrev_b32_e32 v70, 16, v210
	v_and_b32_e32 v71, 0xffff0000, v210
	v_lshlrev_b32_e32 v72, 16, v211
	v_and_b32_e32 v73, 0xffff0000, v211
	v_mul_f32_e32 v64, 0xbfb8aa3b, v70
	v_mul_f32_e32 v65, 0xbfb8aa3b, v71
	v_exp_f32_e32 v64, v64
	v_exp_f32_e32 v65, v65
	v_lshlrev_b32_e32 v74, 16, v212
	v_and_b32_e32 v66, 0xffff0000, v212
	v_add_f32_e32 v64, 1.0, v64
	v_add_f32_e32 v65, 1.0, v65
	v_rcp_f32_e32 v64, v64
	v_rcp_f32_e32 v65, v65
	v_lshlrev_b32_e32 v75, 16, v213
	v_and_b32_e32 v67, 0xffff0000, v213
	v_pk_mul_f32 v[60:61], v[60:61], v[64:65]
	v_mul_f32_e32 v64, 0xbfb8aa3b, v72
	v_mul_f32_e32 v65, 0xbfb8aa3b, v73
	v_exp_f32_e32 v64, v64
	v_exp_f32_e32 v65, v65
	v_add_f32_e32 v64, 1.0, v64
	v_add_f32_e32 v65, 1.0, v65
	v_rcp_f32_e32 v64, v64
	v_rcp_f32_e32 v65, v65
	s_nop 0
	v_pk_mul_f32 v[62:63], v[62:63], v[64:65]
	v_mul_f32_e32 v64, 0xbfb8aa3b, v74
	v_mul_f32_e32 v65, 0xbfb8aa3b, v66
	v_exp_f32_e32 v64, v64
	v_exp_f32_e32 v65, v65
	v_add_f32_e32 v64, 1.0, v64
	v_add_f32_e32 v65, 1.0, v65
	v_rcp_f32_e32 v64, v64
	v_rcp_f32_e32 v65, v65
	s_nop 0
	v_pk_mul_f32 v[56:57], v[56:57], v[64:65]
	v_mul_f32_e32 v64, 0xbfb8aa3b, v75
	v_mul_f32_e32 v65, 0xbfb8aa3b, v67
	v_exp_f32_e32 v64, v64
	v_exp_f32_e32 v65, v65
	v_add_f32_e32 v64, 1.0, v64
	v_add_f32_e32 v65, 1.0, v65
	v_rcp_f32_e32 v64, v64
	v_rcp_f32_e32 v65, v65
	s_nop 0
	v_pk_mul_f32 v[64:65], v[58:59], v[64:65]
	v_cvt_pk_bf16_f32 v58, v60, v61
	v_cvt_pk_bf16_f32 v60, v56, v57
	v_lshl_add_u64 v[56:57], v[122:123], 0, s[0:1]
	s_mov_b32 s0, 0x40000
	v_cvt_pk_bf16_f32 v59, v62, v63
	v_add_co_u32_e32 v62, vcc, s0, v122
	v_cvt_pk_bf16_f32 v61, v64, v65
	s_nop 0
	v_addc_co_u32_e32 v63, vcc, 0, v123, vcc
	global_store_dwordx4 v[62:63], v[58:61], off
	s_nop 1
	v_lshl_add_u64 v[58:59], v[68:69], 0, v[120:121]
	s_waitcnt vmcnt(15)
	v_lshlrev_b32_e32 v62, 16, v214
	v_and_b32_e32 v63, 0xffff0000, v214
	v_lshlrev_b32_e32 v64, 16, v215
	v_and_b32_e32 v65, 0xffff0000, v215
	v_mul_f32_e32 v58, 0xbfb8aa3b, v62
	v_mul_f32_e32 v59, 0xbfb8aa3b, v63
	v_exp_f32_e32 v58, v58
	v_exp_f32_e32 v59, v59
	v_lshlrev_b32_e32 v66, 16, v216
	v_and_b32_e32 v60, 0xffff0000, v216
	v_add_f32_e32 v58, 1.0, v58
	v_add_f32_e32 v59, 1.0, v59
	v_rcp_f32_e32 v58, v58
	v_rcp_f32_e32 v59, v59
	v_lshlrev_b32_e32 v67, 16, v217
	v_and_b32_e32 v61, 0xffff0000, v217
	v_pk_mul_f32 v[52:53], v[52:53], v[58:59]
	v_mul_f32_e32 v58, 0xbfb8aa3b, v64
	v_mul_f32_e32 v59, 0xbfb8aa3b, v65
	v_exp_f32_e32 v58, v58
	v_exp_f32_e32 v59, v59
	v_add_f32_e32 v58, 1.0, v58
	v_add_f32_e32 v59, 1.0, v59
	v_rcp_f32_e32 v58, v58
	v_rcp_f32_e32 v59, v59
	s_nop 0
	v_pk_mul_f32 v[54:55], v[54:55], v[58:59]
	v_mul_f32_e32 v58, 0xbfb8aa3b, v66
	v_mul_f32_e32 v59, 0xbfb8aa3b, v60
	v_exp_f32_e32 v58, v58
	v_exp_f32_e32 v59, v59
	v_add_f32_e32 v58, 1.0, v58
	v_add_f32_e32 v59, 1.0, v59
	v_rcp_f32_e32 v58, v58
	v_rcp_f32_e32 v59, v59
	s_nop 0
	v_pk_mul_f32 v[58:59], v[48:49], v[58:59]
	v_mul_f32_e32 v48, 0xbfb8aa3b, v67
	v_mul_f32_e32 v49, 0xbfb8aa3b, v61
	v_exp_f32_e32 v48, v48
	v_exp_f32_e32 v49, v49
	v_add_f32_e32 v48, 1.0, v48
	v_add_f32_e32 v49, 1.0, v49
	v_rcp_f32_e32 v48, v48
	v_rcp_f32_e32 v49, v49
	s_nop 0
	v_pk_mul_f32 v[60:61], v[50:51], v[48:49]
	v_cvt_pk_bf16_f32 v48, v52, v53
	v_cvt_pk_bf16_f32 v49, v54, v55
	v_cvt_pk_bf16_f32 v50, v58, v59
	v_cvt_pk_bf16_f32 v51, v60, v61
	global_store_dwordx4 v[56:57], v[48:51], off offset:256
	s_mov_b64 s[0:1], 0x90
	s_nop 0
	v_lshl_add_u64 v[50:51], v[130:131], 0, s[0:1]
	v_mad_i64_i32 v[48:49], s[0:1], v50, s10, v[132:133]
	v_lshl_add_u64 v[54:55], v[48:49], 0, s[12:13]
	v_lshlrev_b64 v[50:51], 11, v[50:51]
	v_lshl_add_u64 v[56:57], s[4:5], 0, v[50:51]
	v_lshl_add_u64 v[50:51], v[54:55], 0, v[128:129]
	s_waitcnt vmcnt(15)
	v_lshlrev_b32_e32 v58, 16, v218
	v_and_b32_e32 v59, 0xffff0000, v218
	v_lshlrev_b32_e32 v60, 16, v219
	v_and_b32_e32 v61, 0xffff0000, v219
	v_mul_f32_e32 v50, 0xbfb8aa3b, v58
	v_mul_f32_e32 v51, 0xbfb8aa3b, v59
	v_exp_f32_e32 v50, v50
	v_exp_f32_e32 v51, v51
	v_lshlrev_b32_e32 v62, 16, v220
	v_and_b32_e32 v52, 0xffff0000, v220
	v_add_f32_e32 v50, 1.0, v50
	v_add_f32_e32 v51, 1.0, v51
	v_rcp_f32_e32 v50, v50
	v_rcp_f32_e32 v51, v51
	v_lshlrev_b32_e32 v63, 16, v221
	v_and_b32_e32 v53, 0xffff0000, v221
	v_pk_mul_f32 v[44:45], v[44:45], v[50:51]
	v_mul_f32_e32 v50, 0xbfb8aa3b, v60
	v_mul_f32_e32 v51, 0xbfb8aa3b, v61
	v_exp_f32_e32 v50, v50
	v_exp_f32_e32 v51, v51
	v_add_f32_e32 v50, 1.0, v50
	v_add_f32_e32 v51, 1.0, v51
	v_rcp_f32_e32 v50, v50
	v_rcp_f32_e32 v51, v51
	s_nop 0
	v_pk_mul_f32 v[46:47], v[46:47], v[50:51]
	v_mul_f32_e32 v50, 0xbfb8aa3b, v62
	v_mul_f32_e32 v51, 0xbfb8aa3b, v52
	v_exp_f32_e32 v50, v50
	v_exp_f32_e32 v51, v51
	v_add_f32_e32 v50, 1.0, v50
	v_add_f32_e32 v51, 1.0, v51
	v_rcp_f32_e32 v50, v50
	v_rcp_f32_e32 v51, v51
	s_nop 0
	v_pk_mul_f32 v[40:41], v[40:41], v[50:51]
	v_mul_f32_e32 v50, 0xbfb8aa3b, v63
	v_mul_f32_e32 v51, 0xbfb8aa3b, v53
	v_exp_f32_e32 v50, v50
	v_exp_f32_e32 v51, v51
	v_add_f32_e32 v50, 1.0, v50
	v_add_f32_e32 v51, 1.0, v51
	v_rcp_f32_e32 v50, v50
	v_rcp_f32_e32 v51, v51
	s_nop 0
	v_pk_mul_f32 v[50:51], v[42:43], v[50:51]
	v_cvt_pk_bf16_f32 v42, v44, v45
	v_cvt_pk_bf16_f32 v43, v46, v47
	v_cvt_pk_bf16_f32 v44, v40, v41
	v_cvt_pk_bf16_f32 v45, v50, v51
	v_lshl_add_u64 v[40:41], v[56:57], 0, v[128:129]
	global_store_dwordx4 v[40:41], v[42:45], off
	s_nop 1
	v_lshl_add_u64 v[42:43], v[54:55], 0, v[120:121]
	s_waitcnt vmcnt(15)
	v_lshlrev_b32_e32 v46, 16, v222
	v_and_b32_e32 v47, 0xffff0000, v222
	v_lshlrev_b32_e32 v50, 16, v223
	v_and_b32_e32 v51, 0xffff0000, v223
	v_mul_f32_e32 v42, 0xbfb8aa3b, v46
	v_mul_f32_e32 v43, 0xbfb8aa3b, v47
	v_exp_f32_e32 v42, v42
	v_exp_f32_e32 v43, v43
	v_lshlrev_b32_e32 v52, 16, v224
	v_and_b32_e32 v44, 0xffff0000, v224
	v_add_f32_e32 v42, 1.0, v42
	v_add_f32_e32 v43, 1.0, v43
	v_rcp_f32_e32 v42, v42
	v_rcp_f32_e32 v43, v43
	v_lshlrev_b32_e32 v53, 16, v225
	v_and_b32_e32 v45, 0xffff0000, v225
	v_pk_mul_f32 v[36:37], v[36:37], v[42:43]
	v_mul_f32_e32 v42, 0xbfb8aa3b, v50
	v_mul_f32_e32 v43, 0xbfb8aa3b, v51
	v_exp_f32_e32 v42, v42
	v_exp_f32_e32 v43, v43
	v_add_f32_e32 v42, 1.0, v42
	v_add_f32_e32 v43, 1.0, v43
	v_rcp_f32_e32 v42, v42
	v_rcp_f32_e32 v43, v43
	s_nop 0
	v_pk_mul_f32 v[38:39], v[38:39], v[42:43]
	v_mul_f32_e32 v42, 0xbfb8aa3b, v52
	v_mul_f32_e32 v43, 0xbfb8aa3b, v44
	v_exp_f32_e32 v42, v42
	v_exp_f32_e32 v43, v43
	v_add_f32_e32 v42, 1.0, v42
	v_add_f32_e32 v43, 1.0, v43
	v_rcp_f32_e32 v42, v42
	v_rcp_f32_e32 v43, v43
	s_nop 0
	v_pk_mul_f32 v[42:43], v[32:33], v[42:43]
	v_mul_f32_e32 v32, 0xbfb8aa3b, v53
	v_mul_f32_e32 v33, 0xbfb8aa3b, v45
	v_exp_f32_e32 v32, v32
	v_exp_f32_e32 v33, v33
	v_add_f32_e32 v32, 1.0, v32
	v_add_f32_e32 v33, 1.0, v33
	v_rcp_f32_e32 v32, v32
	v_rcp_f32_e32 v33, v33
	s_nop 0
	v_pk_mul_f32 v[44:45], v[34:35], v[32:33]
	v_cvt_pk_bf16_f32 v32, v36, v37
	v_cvt_pk_bf16_f32 v33, v38, v39
	v_cvt_pk_bf16_f32 v34, v42, v43
	v_cvt_pk_bf16_f32 v35, v44, v45
	global_store_dwordx4 v[40:41], v[32:35], off offset:256
	v_lshl_add_u64 v[36:37], v[48:49], 0, s[14:15]
	s_nop 0
	v_lshl_add_u64 v[32:33], v[36:37], 0, v[128:129]
	s_mov_b64 s[0:1], 0x50000
	s_waitcnt vmcnt(15)
	v_lshlrev_b32_e32 v38, 16, v226
	v_and_b32_e32 v39, 0xffff0000, v226
	v_lshlrev_b32_e32 v40, 16, v227
	v_and_b32_e32 v41, 0xffff0000, v227
	v_mul_f32_e32 v32, 0xbfb8aa3b, v38
	v_mul_f32_e32 v33, 0xbfb8aa3b, v39
	v_exp_f32_e32 v32, v32
	v_exp_f32_e32 v33, v33
	v_lshlrev_b32_e32 v42, 16, v228
	v_and_b32_e32 v34, 0xffff0000, v228
	v_add_f32_e32 v32, 1.0, v32
	v_add_f32_e32 v33, 1.0, v33
	v_rcp_f32_e32 v32, v32
	v_rcp_f32_e32 v33, v33
	v_lshlrev_b32_e32 v43, 16, v229
	v_and_b32_e32 v35, 0xffff0000, v229
	v_pk_mul_f32 v[28:29], v[28:29], v[32:33]
	v_mul_f32_e32 v32, 0xbfb8aa3b, v40
	v_mul_f32_e32 v33, 0xbfb8aa3b, v41
	v_exp_f32_e32 v32, v32
	v_exp_f32_e32 v33, v33
	v_add_f32_e32 v32, 1.0, v32
	v_add_f32_e32 v33, 1.0, v33
	v_rcp_f32_e32 v32, v32
	v_rcp_f32_e32 v33, v33
	s_nop 0
	v_pk_mul_f32 v[30:31], v[30:31], v[32:33]
	v_mul_f32_e32 v32, 0xbfb8aa3b, v42
	v_mul_f32_e32 v33, 0xbfb8aa3b, v34
	v_exp_f32_e32 v32, v32
	v_exp_f32_e32 v33, v33
	v_add_f32_e32 v32, 1.0, v32
	v_add_f32_e32 v33, 1.0, v33
	v_rcp_f32_e32 v32, v32
	v_rcp_f32_e32 v33, v33
	s_nop 0
	v_pk_mul_f32 v[24:25], v[24:25], v[32:33]
	v_mul_f32_e32 v32, 0xbfb8aa3b, v43
	v_mul_f32_e32 v33, 0xbfb8aa3b, v35
	v_exp_f32_e32 v32, v32
	v_exp_f32_e32 v33, v33
	v_add_f32_e32 v32, 1.0, v32
	v_add_f32_e32 v33, 1.0, v33
	v_rcp_f32_e32 v32, v32
	v_rcp_f32_e32 v33, v33
	s_nop 0
	v_pk_mul_f32 v[32:33], v[26:27], v[32:33]
	v_cvt_pk_bf16_f32 v26, v28, v29
	v_cvt_pk_bf16_f32 v28, v24, v25
	v_lshl_add_u64 v[24:25], v[122:123], 0, s[0:1]
	s_mov_b32 s0, 0x50000
	v_cvt_pk_bf16_f32 v27, v30, v31
	v_add_co_u32_e32 v30, vcc, s0, v122
	v_cvt_pk_bf16_f32 v29, v32, v33
	s_nop 0
	v_addc_co_u32_e32 v31, vcc, 0, v123, vcc
	global_store_dwordx4 v[30:31], v[26:29], off
	s_nop 1
	v_lshl_add_u64 v[26:27], v[36:37], 0, v[120:121]
	s_waitcnt vmcnt(15)
	v_lshlrev_b32_e32 v30, 16, v230
	v_and_b32_e32 v31, 0xffff0000, v230
	v_lshlrev_b32_e32 v32, 16, v231
	v_and_b32_e32 v33, 0xffff0000, v231
	v_mul_f32_e32 v26, 0xbfb8aa3b, v30
	v_mul_f32_e32 v27, 0xbfb8aa3b, v31
	v_exp_f32_e32 v26, v26
	v_exp_f32_e32 v27, v27
	v_lshlrev_b32_e32 v34, 16, v232
	v_and_b32_e32 v28, 0xffff0000, v232
	v_add_f32_e32 v26, 1.0, v26
	v_add_f32_e32 v27, 1.0, v27
	v_rcp_f32_e32 v26, v26
	v_rcp_f32_e32 v27, v27
	v_lshlrev_b32_e32 v35, 16, v233
	v_and_b32_e32 v29, 0xffff0000, v233
	v_pk_mul_f32 v[20:21], v[20:21], v[26:27]
	v_mul_f32_e32 v26, 0xbfb8aa3b, v32
	v_mul_f32_e32 v27, 0xbfb8aa3b, v33
	v_exp_f32_e32 v26, v26
	v_exp_f32_e32 v27, v27
	v_add_f32_e32 v26, 1.0, v26
	v_add_f32_e32 v27, 1.0, v27
	v_rcp_f32_e32 v26, v26
	v_rcp_f32_e32 v27, v27
	s_nop 0
	v_pk_mul_f32 v[22:23], v[22:23], v[26:27]
	v_mul_f32_e32 v26, 0xbfb8aa3b, v34
	v_mul_f32_e32 v27, 0xbfb8aa3b, v28
	v_exp_f32_e32 v26, v26
	v_exp_f32_e32 v27, v27
	v_add_f32_e32 v26, 1.0, v26
	v_add_f32_e32 v27, 1.0, v27
	v_rcp_f32_e32 v26, v26
	v_rcp_f32_e32 v27, v27
	s_nop 0
	v_pk_mul_f32 v[26:27], v[16:17], v[26:27]
	v_mul_f32_e32 v16, 0xbfb8aa3b, v35
	v_mul_f32_e32 v17, 0xbfb8aa3b, v29
	v_exp_f32_e32 v16, v16
	v_exp_f32_e32 v17, v17
	v_add_f32_e32 v16, 1.0, v16
	v_add_f32_e32 v17, 1.0, v17
	v_rcp_f32_e32 v16, v16
	v_rcp_f32_e32 v17, v17
	s_nop 0
	v_pk_mul_f32 v[28:29], v[18:19], v[16:17]
	v_cvt_pk_bf16_f32 v16, v20, v21
	v_cvt_pk_bf16_f32 v17, v22, v23
	v_cvt_pk_bf16_f32 v18, v26, v27
	v_cvt_pk_bf16_f32 v19, v28, v29
	global_store_dwordx4 v[24:25], v[16:19], off offset:256
	v_lshl_add_u64 v[20:21], v[48:49], 0, s[26:27]
	s_nop 0
	v_lshl_add_u64 v[16:17], v[20:21], 0, v[128:129]
	s_mov_b64 s[0:1], 0x58000
	s_waitcnt vmcnt(15)
	v_lshlrev_b32_e32 v22, 16, v234
	v_and_b32_e32 v23, 0xffff0000, v234
	v_lshlrev_b32_e32 v24, 16, v235
	v_and_b32_e32 v25, 0xffff0000, v235
	v_mul_f32_e32 v16, 0xbfb8aa3b, v22
	v_mul_f32_e32 v17, 0xbfb8aa3b, v23
	v_exp_f32_e32 v16, v16
	v_exp_f32_e32 v17, v17
	v_lshlrev_b32_e32 v26, 16, v236
	v_and_b32_e32 v18, 0xffff0000, v236
	v_add_f32_e32 v16, 1.0, v16
	v_add_f32_e32 v17, 1.0, v17
	v_rcp_f32_e32 v16, v16
	v_rcp_f32_e32 v17, v17
	v_lshlrev_b32_e32 v27, 16, v237
	v_and_b32_e32 v19, 0xffff0000, v237
	v_pk_mul_f32 v[12:13], v[12:13], v[16:17]
	v_mul_f32_e32 v16, 0xbfb8aa3b, v24
	v_mul_f32_e32 v17, 0xbfb8aa3b, v25
	v_exp_f32_e32 v16, v16
	v_exp_f32_e32 v17, v17
	v_add_f32_e32 v16, 1.0, v16
	v_add_f32_e32 v17, 1.0, v17
	v_rcp_f32_e32 v16, v16
	v_rcp_f32_e32 v17, v17
	s_nop 0
	v_pk_mul_f32 v[14:15], v[14:15], v[16:17]
	v_mul_f32_e32 v16, 0xbfb8aa3b, v26
	v_mul_f32_e32 v17, 0xbfb8aa3b, v18
	v_exp_f32_e32 v16, v16
	v_exp_f32_e32 v17, v17
	v_add_f32_e32 v16, 1.0, v16
	v_add_f32_e32 v17, 1.0, v17
	v_rcp_f32_e32 v16, v16
	v_rcp_f32_e32 v17, v17
	s_nop 0
	v_pk_mul_f32 v[8:9], v[8:9], v[16:17]
	v_mul_f32_e32 v16, 0xbfb8aa3b, v27
	v_mul_f32_e32 v17, 0xbfb8aa3b, v19
	v_exp_f32_e32 v16, v16
	v_exp_f32_e32 v17, v17
	v_add_f32_e32 v16, 1.0, v16
	v_add_f32_e32 v17, 1.0, v17
	v_rcp_f32_e32 v16, v16
	v_rcp_f32_e32 v17, v17
	s_nop 0
	v_pk_mul_f32 v[16:17], v[10:11], v[16:17]
	v_cvt_pk_bf16_f32 v10, v12, v13
	v_cvt_pk_bf16_f32 v12, v8, v9
	v_lshl_add_u64 v[8:9], v[122:123], 0, s[0:1]
	s_mov_b32 s0, 0x58000
	v_cvt_pk_bf16_f32 v11, v14, v15
	v_add_co_u32_e32 v14, vcc, s0, v122
	v_cvt_pk_bf16_f32 v13, v16, v17
	s_nop 0
	v_addc_co_u32_e32 v15, vcc, 0, v123, vcc
	global_store_dwordx4 v[14:15], v[10:13], off
	s_nop 1
	v_lshl_add_u64 v[10:11], v[20:21], 0, v[120:121]
	s_waitcnt vmcnt(15)
	v_lshlrev_b32_e32 v14, 16, v238
	v_and_b32_e32 v15, 0xffff0000, v238
	v_lshlrev_b32_e32 v16, 16, v239
	v_and_b32_e32 v17, 0xffff0000, v239
	v_mul_f32_e32 v10, 0xbfb8aa3b, v14
	v_mul_f32_e32 v11, 0xbfb8aa3b, v15
	v_exp_f32_e32 v10, v10
	v_exp_f32_e32 v11, v11
	v_lshlrev_b32_e32 v18, 16, v240
	v_and_b32_e32 v12, 0xffff0000, v240
	v_add_f32_e32 v10, 1.0, v10
	v_add_f32_e32 v11, 1.0, v11
	v_rcp_f32_e32 v10, v10
	v_rcp_f32_e32 v11, v11
	v_lshlrev_b32_e32 v19, 16, v241
	v_and_b32_e32 v13, 0xffff0000, v241
	v_pk_mul_f32 v[4:5], v[4:5], v[10:11]
	v_mul_f32_e32 v10, 0xbfb8aa3b, v16
	v_mul_f32_e32 v11, 0xbfb8aa3b, v17
	v_exp_f32_e32 v10, v10
	v_exp_f32_e32 v11, v11
	v_add_f32_e32 v10, 1.0, v10
	v_add_f32_e32 v11, 1.0, v11
	v_rcp_f32_e32 v10, v10
	v_rcp_f32_e32 v11, v11
	s_nop 0
	v_pk_mul_f32 v[6:7], v[6:7], v[10:11]
	v_mul_f32_e32 v10, 0xbfb8aa3b, v18
	v_mul_f32_e32 v11, 0xbfb8aa3b, v12
	v_exp_f32_e32 v10, v10
	v_exp_f32_e32 v11, v11
	v_add_f32_e32 v10, 1.0, v10
	v_add_f32_e32 v11, 1.0, v11
	v_rcp_f32_e32 v10, v10
	v_rcp_f32_e32 v11, v11
	s_nop 0
	v_pk_mul_f32 v[10:11], v[0:1], v[10:11]
	v_mul_f32_e32 v0, 0xbfb8aa3b, v19
	v_mul_f32_e32 v1, 0xbfb8aa3b, v13
	v_exp_f32_e32 v0, v0
	v_exp_f32_e32 v1, v1
	v_add_f32_e32 v0, 1.0, v0
	v_add_f32_e32 v1, 1.0, v1
	v_rcp_f32_e32 v0, v0
	v_rcp_f32_e32 v1, v1
	s_nop 0
	v_pk_mul_f32 v[12:13], v[2:3], v[0:1]
	v_cvt_pk_bf16_f32 v0, v4, v5
	v_cvt_pk_bf16_f32 v1, v6, v7
	v_cvt_pk_bf16_f32 v2, v10, v11
	v_cvt_pk_bf16_f32 v3, v12, v13
	global_store_dwordx4 v[8:9], v[0:3], off offset:256
	s_add_i32 s6, s6, s74
	s_add_i32 s9, s9, s20
	s_cmpk_gt_i32 s6, 0xff
	s_cbranch_scc1 .LBB0_546
